# P6 epilogue: coalesced bf16 stores + nt hint on the UP stores
# baseline (speedup 1.0000x reference)
.LBB0_731:
	ds_read_b128 v[148:151], v156
	ds_read_b128 v[160:163], v156 offset:1024
	ds_read_b128 v[164:167], v156 offset:2048
	ds_read_b128 v[168:171], v156 offset:3072
	ds_read_b128 v[176:179], v157
	ds_read_b128 v[180:183], v157 offset:1024
	ds_read_b128 v[184:187], v157 offset:2048
	ds_read_b128 v[188:191], v157 offset:3072
	s_add_u32 s22, s0, 0xfff00080
	s_addc_u32 s23, s1, -1
	s_cmp_eq_u32 s61, 60
	s_cselect_b32 s25, s5, s23
	s_cselect_b32 s24, s57, s22
	s_cselect_b32 s23, s21, s60
	s_cselect_b32 s22, s58, s59
	v_lshl_add_u64 v[152:153], s[0:1], 0, v[140:141]
	s_add_i32 m0, s34, 0xc000
	ds_read_b128 v[192:195], v158
	ds_read_b128 v[196:199], v158 offset:1024
	ds_read_b128 v[200:203], v158 offset:2048
	ds_read_b128 v[204:207], v158 offset:3072
	ds_read_b128 v[208:211], v158 offset:4096
	ds_read_b128 v[212:215], v158 offset:5120
	ds_read_b128 v[216:219], v158 offset:6144
	ds_read_b128 v[220:223], v158 offset:7168
	global_load_lds_dwordx4 v[152:153], off
	v_lshl_add_u64 v[152:153], s[0:1], 0, v[142:143]
	s_add_i32 m0, s34, 0xe000
	s_nop 0
	global_load_lds_dwordx4 v[152:153], off
	s_waitcnt vmcnt(8)
	s_waitcnt lgkmcnt(0)
	s_barrier
	s_setprio 1
	s_waitcnt lgkmcnt(0)
	v_mfma_f32_16x16x32_bf16 v[126:129], v[148:151], v[192:195], v[126:129]
	v_mfma_f32_16x16x32_bf16 v[122:125], v[164:167], v[192:195], v[122:125]
	v_mfma_f32_16x16x32_bf16 v[110:113], v[148:151], v[200:203], v[110:113]
	v_mfma_f32_16x16x32_bf16 v[106:109], v[164:167], v[200:203], v[106:109]
	v_mfma_f32_16x16x32_bf16 v[94:97], v[148:151], v[208:211], v[94:97]
	v_mfma_f32_16x16x32_bf16 v[90:93], v[164:167], v[208:211], v[90:93]
	v_mfma_f32_16x16x32_bf16 v[78:81], v[148:151], v[216:219], v[78:81]
	v_mfma_f32_16x16x32_bf16 v[74:77], v[164:167], v[216:219], v[74:77]
	v_mfma_f32_16x16x32_bf16 v[126:129], v[160:163], v[196:199], v[126:129]
	v_mfma_f32_16x16x32_bf16 v[122:125], v[168:171], v[196:199], v[122:125]
	v_mfma_f32_16x16x32_bf16 v[110:113], v[160:163], v[204:207], v[110:113]
	v_mfma_f32_16x16x32_bf16 v[106:109], v[168:171], v[204:207], v[106:109]
	v_mfma_f32_16x16x32_bf16 v[94:97], v[160:163], v[212:215], v[94:97]
	v_mfma_f32_16x16x32_bf16 v[90:93], v[168:171], v[212:215], v[90:93]
	v_mfma_f32_16x16x32_bf16 v[78:81], v[160:163], v[220:223], v[78:81]
	v_mfma_f32_16x16x32_bf16 v[74:77], v[168:171], v[220:223], v[74:77]
	s_setprio 0
	s_setprio 1
	v_mfma_f32_16x16x32_bf16 v[118:121], v[176:179], v[192:195], v[118:121]
	v_mfma_f32_16x16x32_bf16 v[114:117], v[184:187], v[192:195], v[114:117]
	v_mfma_f32_16x16x32_bf16 v[102:105], v[176:179], v[200:203], v[102:105]
	v_mfma_f32_16x16x32_bf16 v[98:101], v[184:187], v[200:203], v[98:101]
	v_mfma_f32_16x16x32_bf16 v[86:89], v[176:179], v[208:211], v[86:89]
	v_mfma_f32_16x16x32_bf16 v[82:85], v[184:187], v[208:211], v[82:85]
	v_mfma_f32_16x16x32_bf16 v[70:73], v[176:179], v[216:219], v[70:73]
	v_mfma_f32_16x16x32_bf16 v[66:69], v[184:187], v[216:219], v[66:69]
	v_mfma_f32_16x16x32_bf16 v[118:121], v[180:183], v[196:199], v[118:121]
	v_mfma_f32_16x16x32_bf16 v[114:117], v[188:191], v[196:199], v[114:117]
	v_mfma_f32_16x16x32_bf16 v[102:105], v[180:183], v[204:207], v[102:105]
	v_mfma_f32_16x16x32_bf16 v[98:101], v[188:191], v[204:207], v[98:101]
	v_mfma_f32_16x16x32_bf16 v[86:89], v[180:183], v[212:215], v[86:89]
	v_mfma_f32_16x16x32_bf16 v[82:85], v[188:191], v[212:215], v[82:85]
	v_mfma_f32_16x16x32_bf16 v[70:73], v[180:183], v[220:223], v[70:73]
	v_mfma_f32_16x16x32_bf16 v[66:69], v[188:191], v[220:223], v[66:69]
	s_setprio 0
	s_barrier
	s_add_i32 s62, s44, s31
	v_lshl_add_u64 v[152:153], s[22:23], 0, v[136:137]
	s_mov_b32 m0, s62
	ds_read_b128 v[192:195], v158 offset:16384
	ds_read_b128 v[196:199], v158 offset:17408
	ds_read_b128 v[200:203], v158 offset:18432
	ds_read_b128 v[204:207], v158 offset:19456
	ds_read_b128 v[208:211], v158 offset:20480
	ds_read_b128 v[212:215], v158 offset:21504
	ds_read_b128 v[216:219], v158 offset:22528
	ds_read_b128 v[220:223], v158 offset:23552
	global_load_lds_dwordx4 v[152:153], off
	s_add_i32 m0, s62, 0x2000
	s_add_u32 s62, s22, 0x100000
	v_lshl_add_u64 v[172:173], s[22:23], 0, v[130:131]
	s_addc_u32 s63, s23, 0
	s_add_i32 s64, s45, s31
	global_load_lds_dwordx4 v[172:173], off
	v_lshl_add_u64 v[224:225], s[62:63], 0, v[136:137]
	s_mov_b32 m0, s64
	v_lshl_add_u64 v[226:227], s[24:25], 0, v[132:133]
	global_load_lds_dwordx4 v[224:225], off
	v_lshl_add_u64 v[224:225], s[62:63], 0, v[130:131]
	s_add_i32 m0, s64, 0x2000
	s_nop 0
	global_load_lds_dwordx4 v[224:225], off
	v_lshl_add_u64 v[224:225], s[24:25], 0, v[138:139]
	s_mov_b32 m0, s34
	s_nop 0
	global_load_lds_dwordx4 v[224:225], off
	s_mov_b32 m0, s35
	s_nop 0
	global_load_lds_dwordx4 v[226:227], off
	s_waitcnt vmcnt(8)
	s_waitcnt lgkmcnt(0)
	s_barrier
	s_setprio 1
	s_waitcnt lgkmcnt(0)
	v_mfma_f32_16x16x32_bf16 v[62:65], v[148:151], v[192:195], v[62:65]
	v_mfma_f32_16x16x32_bf16 v[58:61], v[164:167], v[192:195], v[58:61]
	v_mfma_f32_16x16x32_bf16 v[46:49], v[148:151], v[200:203], v[46:49]
	v_mfma_f32_16x16x32_bf16 v[42:45], v[164:167], v[200:203], v[42:45]
	v_mfma_f32_16x16x32_bf16 v[30:33], v[148:151], v[208:211], v[30:33]
	v_mfma_f32_16x16x32_bf16 v[26:29], v[164:167], v[208:211], v[26:29]
	v_mfma_f32_16x16x32_bf16 v[14:17], v[148:151], v[216:219], v[14:17]
	v_mfma_f32_16x16x32_bf16 v[10:13], v[164:167], v[216:219], v[10:13]
	v_mfma_f32_16x16x32_bf16 v[62:65], v[160:163], v[196:199], v[62:65]
	v_mfma_f32_16x16x32_bf16 v[58:61], v[168:171], v[196:199], v[58:61]
	v_mfma_f32_16x16x32_bf16 v[46:49], v[160:163], v[204:207], v[46:49]
	v_mfma_f32_16x16x32_bf16 v[42:45], v[168:171], v[204:207], v[42:45]
	v_mfma_f32_16x16x32_bf16 v[30:33], v[160:163], v[212:215], v[30:33]
	v_mfma_f32_16x16x32_bf16 v[26:29], v[168:171], v[212:215], v[26:29]
	v_mfma_f32_16x16x32_bf16 v[14:17], v[160:163], v[220:223], v[14:17]
	v_mfma_f32_16x16x32_bf16 v[10:13], v[168:171], v[220:223], v[10:13]
	s_setprio 0
	s_setprio 1
	v_mfma_f32_16x16x32_bf16 v[54:57], v[176:179], v[192:195], v[54:57]
	v_mfma_f32_16x16x32_bf16 v[50:53], v[184:187], v[192:195], v[50:53]
	v_mfma_f32_16x16x32_bf16 v[38:41], v[176:179], v[200:203], v[38:41]
	v_mfma_f32_16x16x32_bf16 v[34:37], v[184:187], v[200:203], v[34:37]
	v_mfma_f32_16x16x32_bf16 v[22:25], v[176:179], v[208:211], v[22:25]
	v_mfma_f32_16x16x32_bf16 v[18:21], v[184:187], v[208:211], v[18:21]
	v_mfma_f32_16x16x32_bf16 v[6:9], v[176:179], v[216:219], v[6:9]
	v_mfma_f32_16x16x32_bf16 v[2:5], v[184:187], v[216:219], v[2:5]
	v_mfma_f32_16x16x32_bf16 v[54:57], v[180:183], v[196:199], v[54:57]
	v_mfma_f32_16x16x32_bf16 v[50:53], v[188:191], v[196:199], v[50:53]
	v_mfma_f32_16x16x32_bf16 v[38:41], v[180:183], v[204:207], v[38:41]
	v_mfma_f32_16x16x32_bf16 v[34:37], v[188:191], v[204:207], v[34:37]
	v_mfma_f32_16x16x32_bf16 v[22:25], v[180:183], v[212:215], v[22:25]
	v_mfma_f32_16x16x32_bf16 v[18:21], v[188:191], v[212:215], v[18:21]
	v_mfma_f32_16x16x32_bf16 v[6:9], v[180:183], v[220:223], v[6:9]
	v_mfma_f32_16x16x32_bf16 v[2:5], v[188:191], v[220:223], v[2:5]
	s_setprio 0
	s_barrier
	s_add_i32 s62, 0, 0x18000
	v_add_u32_e32 v159, s62, v135
	s_add_i32 s63, 0, 0x1c000
	ds_read_b128 v[148:151], v159
	ds_read_b128 v[160:163], v159 offset:1024
	ds_read_b128 v[164:167], v159 offset:2048
	ds_read_b128 v[168:171], v159 offset:3072
	v_add_u32_e32 v159, s63, v135
	ds_read_b128 v[176:179], v159
	ds_read_b128 v[180:183], v159 offset:1024
	ds_read_b128 v[184:187], v159 offset:2048
	ds_read_b128 v[188:191], v159 offset:3072
	s_add_u32 s24, s24, 0x100000
	s_addc_u32 s25, s25, 0
	s_mov_b32 m0, s36
	v_lshl_add_u64 v[228:229], s[24:25], 0, v[138:139]
	ds_read_b128 v[192:195], v158 offset:32768
	ds_read_b128 v[196:199], v158 offset:33792
	ds_read_b128 v[200:203], v158 offset:34816
	ds_read_b128 v[204:207], v158 offset:35840
	ds_read_b128 v[208:211], v158 offset:36864
	ds_read_b128 v[212:215], v158 offset:37888
	ds_read_b128 v[216:219], v158 offset:38912
	ds_read_b128 v[220:223], v158 offset:39936
	global_load_lds_dwordx4 v[228:229], off
	v_lshl_add_u64 v[228:229], s[24:25], 0, v[132:133]
	s_mov_b32 m0, s37
	s_nop 0
	global_load_lds_dwordx4 v[228:229], off
	s_waitcnt vmcnt(8)
	s_waitcnt lgkmcnt(0)
	s_barrier
	s_setprio 1
	s_waitcnt lgkmcnt(0)
	v_mfma_f32_16x16x32_bf16 v[126:129], v[148:151], v[192:195], v[126:129]
	v_mfma_f32_16x16x32_bf16 v[122:125], v[164:167], v[192:195], v[122:125]
	v_mfma_f32_16x16x32_bf16 v[110:113], v[148:151], v[200:203], v[110:113]
	v_mfma_f32_16x16x32_bf16 v[106:109], v[164:167], v[200:203], v[106:109]
	v_mfma_f32_16x16x32_bf16 v[94:97], v[148:151], v[208:211], v[94:97]
	v_mfma_f32_16x16x32_bf16 v[90:93], v[164:167], v[208:211], v[90:93]
	v_mfma_f32_16x16x32_bf16 v[78:81], v[148:151], v[216:219], v[78:81]
	v_mfma_f32_16x16x32_bf16 v[74:77], v[164:167], v[216:219], v[74:77]
	v_mfma_f32_16x16x32_bf16 v[126:129], v[160:163], v[196:199], v[126:129]
	v_mfma_f32_16x16x32_bf16 v[122:125], v[168:171], v[196:199], v[122:125]
	v_mfma_f32_16x16x32_bf16 v[110:113], v[160:163], v[204:207], v[110:113]
	v_mfma_f32_16x16x32_bf16 v[106:109], v[168:171], v[204:207], v[106:109]
	v_mfma_f32_16x16x32_bf16 v[94:97], v[160:163], v[212:215], v[94:97]
	v_mfma_f32_16x16x32_bf16 v[90:93], v[168:171], v[212:215], v[90:93]
	v_mfma_f32_16x16x32_bf16 v[78:81], v[160:163], v[220:223], v[78:81]
	v_mfma_f32_16x16x32_bf16 v[74:77], v[168:171], v[220:223], v[74:77]
	s_setprio 0
	s_setprio 1
	v_mfma_f32_16x16x32_bf16 v[118:121], v[176:179], v[192:195], v[118:121]
	v_mfma_f32_16x16x32_bf16 v[114:117], v[184:187], v[192:195], v[114:117]
	v_mfma_f32_16x16x32_bf16 v[102:105], v[176:179], v[200:203], v[102:105]
	v_mfma_f32_16x16x32_bf16 v[98:101], v[184:187], v[200:203], v[98:101]
	v_mfma_f32_16x16x32_bf16 v[86:89], v[176:179], v[208:211], v[86:89]
	v_mfma_f32_16x16x32_bf16 v[82:85], v[184:187], v[208:211], v[82:85]
	v_mfma_f32_16x16x32_bf16 v[70:73], v[176:179], v[216:219], v[70:73]
	v_mfma_f32_16x16x32_bf16 v[66:69], v[184:187], v[216:219], v[66:69]
	v_mfma_f32_16x16x32_bf16 v[118:121], v[180:183], v[196:199], v[118:121]
	v_mfma_f32_16x16x32_bf16 v[114:117], v[188:191], v[196:199], v[114:117]
	v_mfma_f32_16x16x32_bf16 v[102:105], v[180:183], v[204:207], v[102:105]
	v_mfma_f32_16x16x32_bf16 v[98:101], v[188:191], v[204:207], v[98:101]
	v_mfma_f32_16x16x32_bf16 v[86:89], v[180:183], v[212:215], v[86:89]
	v_mfma_f32_16x16x32_bf16 v[82:85], v[188:191], v[212:215], v[82:85]
	v_mfma_f32_16x16x32_bf16 v[70:73], v[180:183], v[220:223], v[70:73]
	v_mfma_f32_16x16x32_bf16 v[66:69], v[188:191], v[220:223], v[66:69]
	s_setprio 0
	s_barrier
	s_add_i32 s24, s62, s31
	v_lshl_add_u64 v[152:153], v[152:153], 0, s[16:17]
	s_mov_b32 m0, s24
	ds_read_b128 v[192:195], v158 offset:49152
	ds_read_b128 v[196:199], v158 offset:50176
	ds_read_b128 v[200:203], v158 offset:51200
	ds_read_b128 v[204:207], v158 offset:52224
	ds_read_b128 v[208:211], v158 offset:53248
	ds_read_b128 v[212:215], v158 offset:54272
	ds_read_b128 v[216:219], v158 offset:55296
	ds_read_b128 v[220:223], v158 offset:56320
	global_load_lds_dwordx4 v[152:153], off
	s_add_i32 m0, s24, 0x2000
	s_add_u32 s22, s22, 0x100080
	v_lshl_add_u64 v[152:153], v[172:173], 0, s[16:17]
	s_addc_u32 s23, s23, 0
	s_add_i32 s24, s63, s31
	global_load_lds_dwordx4 v[152:153], off
	v_lshl_add_u64 v[152:153], s[22:23], 0, v[136:137]
	s_mov_b32 m0, s24
	s_nop 0
	global_load_lds_dwordx4 v[152:153], off
	v_lshl_add_u64 v[152:153], s[22:23], 0, v[130:131]
	s_add_i32 m0, s24, 0x2000
	s_nop 0
	global_load_lds_dwordx4 v[152:153], off
	v_lshl_add_u64 v[152:153], v[224:225], 0, s[16:17]
	s_mov_b32 m0, s40
	s_nop 0
	global_load_lds_dwordx4 v[152:153], off
	v_lshl_add_u64 v[152:153], v[226:227], 0, s[16:17]
	s_mov_b32 m0, s41
	s_nop 0
	global_load_lds_dwordx4 v[152:153], off
	s_waitcnt vmcnt(8)
	s_waitcnt lgkmcnt(0)
	s_barrier
	s_setprio 1
	s_waitcnt lgkmcnt(0)
	v_mfma_f32_16x16x32_bf16 v[62:65], v[148:151], v[192:195], v[62:65]
	v_mfma_f32_16x16x32_bf16 v[58:61], v[164:167], v[192:195], v[58:61]
	v_mfma_f32_16x16x32_bf16 v[46:49], v[148:151], v[200:203], v[46:49]
	v_mfma_f32_16x16x32_bf16 v[42:45], v[164:167], v[200:203], v[42:45]
	v_mfma_f32_16x16x32_bf16 v[30:33], v[148:151], v[208:211], v[30:33]
	v_mfma_f32_16x16x32_bf16 v[26:29], v[164:167], v[208:211], v[26:29]
	v_mfma_f32_16x16x32_bf16 v[14:17], v[148:151], v[216:219], v[14:17]
	v_mfma_f32_16x16x32_bf16 v[10:13], v[164:167], v[216:219], v[10:13]
	v_mfma_f32_16x16x32_bf16 v[62:65], v[160:163], v[196:199], v[62:65]
	v_mfma_f32_16x16x32_bf16 v[58:61], v[168:171], v[196:199], v[58:61]
	v_mfma_f32_16x16x32_bf16 v[46:49], v[160:163], v[204:207], v[46:49]
	v_mfma_f32_16x16x32_bf16 v[42:45], v[168:171], v[204:207], v[42:45]
	v_mfma_f32_16x16x32_bf16 v[30:33], v[160:163], v[212:215], v[30:33]
	v_mfma_f32_16x16x32_bf16 v[26:29], v[168:171], v[212:215], v[26:29]
	v_mfma_f32_16x16x32_bf16 v[14:17], v[160:163], v[220:223], v[14:17]
	v_mfma_f32_16x16x32_bf16 v[10:13], v[168:171], v[220:223], v[10:13]
	s_setprio 0
	s_setprio 1
	v_mfma_f32_16x16x32_bf16 v[54:57], v[176:179], v[192:195], v[54:57]
	v_mfma_f32_16x16x32_bf16 v[50:53], v[184:187], v[192:195], v[50:53]
	v_mfma_f32_16x16x32_bf16 v[38:41], v[176:179], v[200:203], v[38:41]
	v_mfma_f32_16x16x32_bf16 v[34:37], v[184:187], v[200:203], v[34:37]
	v_mfma_f32_16x16x32_bf16 v[22:25], v[176:179], v[208:211], v[22:25]
	v_mfma_f32_16x16x32_bf16 v[18:21], v[184:187], v[208:211], v[18:21]
	v_mfma_f32_16x16x32_bf16 v[6:9], v[176:179], v[216:219], v[6:9]
	v_mfma_f32_16x16x32_bf16 v[2:5], v[184:187], v[216:219], v[2:5]
	v_mfma_f32_16x16x32_bf16 v[54:57], v[180:183], v[196:199], v[54:57]
	v_mfma_f32_16x16x32_bf16 v[50:53], v[188:191], v[196:199], v[50:53]
	v_mfma_f32_16x16x32_bf16 v[38:41], v[180:183], v[204:207], v[38:41]
	v_mfma_f32_16x16x32_bf16 v[34:37], v[188:191], v[204:207], v[34:37]
	v_mfma_f32_16x16x32_bf16 v[22:25], v[180:183], v[212:215], v[22:25]
	v_mfma_f32_16x16x32_bf16 v[18:21], v[188:191], v[212:215], v[18:21]
	v_mfma_f32_16x16x32_bf16 v[6:9], v[180:183], v[220:223], v[6:9]
	v_mfma_f32_16x16x32_bf16 v[2:5], v[188:191], v[220:223], v[2:5]
	s_setprio 0
	s_barrier
	s_add_i32 s61, s61, 2
	s_add_u32 s0, s0, 0x100
	s_addc_u32 s1, s1, 0
	s_add_u32 s59, s59, 0x100
	s_addc_u32 s60, s60, 0
	s_cmp_gt_u32 s61, 61
	s_cbranch_scc0 .LBB0_731
	v_and_b32_e32 v165, 3, v174
	v_lshrrev_b32_e32 v170, 2, v174
	v_lshlrev_b32_e32 v164, 6, v165
	v_and_or_b32 v164, v174, 60, v164
	v_and_b32_e32 v171, 15, v174
	v_sub_u32_e32 v170, v170, v171
	v_lshrrev_b32_e32 v171, 4, v174
	v_sub_u32_e32 v165, v165, v171
	v_mul_i32_i24_e32 v170, 0xac00, v170
	v_lshl_add_u32 v166, v165, 4, v170
	v_ashrrev_i32_e32 v167, 31, v166
	s_lshl_b32 s5, s56, 8
	s_add_i32 s5, s5, s39
	v_or_b32_e32 v159, s5, v1
	v_cmp_lt_i32_e64 s[0:1], s46, v159
	s_and_b64 s[22:23], s[0:1], s[18:19]
	v_mov_b64_e32 v[150:151], 0
	s_and_saveexec_b64 s[0:1], s[22:23]
	v_add_u32_e32 v148, 0xffffe000, v159
	v_lshrrev_b32_e32 v148, 2, v148
	v_and_b32_e32 v148, 0x3ffffff2, v148
	v_add_u32_e32 v150, v148, v154
	v_mov_b64_e32 v[148:149], s[10:11]
	v_mad_u64_u32 v[150:151], s[22:23], v150, s47, v[148:149]
	s_or_b64 exec, exec, s[0:1]
	v_lshl_or_b32 v148, s55, 8, v155
	v_mov_b64_e32 v[152:153], s[6:7]
	v_ashrrev_i32_e32 v149, 31, v148
	v_mad_i64_i32 v[152:153], s[0:1], v159, s48, v[152:153]
	v_lshl_add_u64 v[152:153], v[148:149], 1, v[152:153]
	v_cmp_ne_u64_e64 s[0:1], 0, v[150:151]
	v_lshl_add_u64 v[150:151], v[148:149], 2, v[150:151]
	v_cvt_pk_bf16_f32 v160, v126, v127
	v_cvt_pk_bf16_f32 v161, v128, v129
	v_cvt_pk_bf16_f32 v162, v122, v123
	v_cvt_pk_bf16_f32 v163, v124, v125
	ds_bpermute_b32 v160, v164, v160
	ds_bpermute_b32 v161, v164, v161
	ds_bpermute_b32 v162, v164, v162
	ds_bpermute_b32 v163, v164, v163
	v_lshl_add_u64 v[168:169], v[166:167], 0, v[152:153]
	s_waitcnt lgkmcnt(0)
	global_store_dwordx4 v[168:169], v[160:163], off nt
	s_and_saveexec_b64 s[22:23], s[0:1]
	s_cbranch_execz .LBB0_736
	global_store_dwordx4 v[150:151], v[126:129], off
	global_store_dwordx4 v[150:151], v[122:125], off offset:16
.LBB0_736:
	s_or_b64 exec, exec, s[22:23]
	s_nop 0
	v_cvt_pk_bf16_f32 v122, v118, v119
	v_cvt_pk_bf16_f32 v123, v120, v121
	v_cvt_pk_bf16_f32 v124, v114, v115
	v_cvt_pk_bf16_f32 v125, v116, v117
	ds_bpermute_b32 v122, v164, v122
	ds_bpermute_b32 v123, v164, v123
	ds_bpermute_b32 v124, v164, v124
	ds_bpermute_b32 v125, v164, v125
	v_lshl_add_u64 v[168:169], v[166:167], 0, v[152:153]
	s_waitcnt lgkmcnt(0)
	global_store_dwordx4 v[168:169], v[122:125], off offset:256 nt
	s_and_saveexec_b64 s[22:23], s[0:1]
	s_cbranch_execz .LBB0_738
	global_store_dwordx4 v[150:151], v[118:121], off offset:512
	global_store_dwordx4 v[150:151], v[114:117], off offset:528
.LBB0_738:
	s_or_b64 exec, exec, s[22:23]
	s_nop 0
	v_or_b32_e32 v116, 16, v159
	v_cmp_lt_i32_e64 s[0:1], s46, v116
	s_and_b64 s[22:23], s[0:1], s[18:19]
	v_mov_b64_e32 v[114:115], 0
	s_and_saveexec_b64 s[0:1], s[22:23]
	v_add_u32_e32 v114, 0xffffe010, v159
	v_lshrrev_b32_e32 v114, 2, v114
	v_and_b32_e32 v114, 0x3ffffff6, v114
	v_add_u32_e32 v117, v114, v154
	v_mov_b64_e32 v[114:115], s[10:11]
	v_mad_u64_u32 v[114:115], s[22:23], v117, s47, v[114:115]
	s_or_b64 exec, exec, s[0:1]
	v_mov_b64_e32 v[118:119], s[6:7]
	v_mad_i64_i32 v[116:117], s[0:1], v116, s48, v[118:119]
	v_lshl_add_u64 v[116:117], v[148:149], 1, v[116:117]
	v_cmp_ne_u64_e64 s[0:1], 0, v[114:115]
	v_lshl_add_u64 v[114:115], v[148:149], 2, v[114:115]
	v_cvt_pk_bf16_f32 v118, v110, v111
	v_cvt_pk_bf16_f32 v119, v112, v113
	v_cvt_pk_bf16_f32 v120, v106, v107
	v_cvt_pk_bf16_f32 v121, v108, v109
	ds_bpermute_b32 v118, v164, v118
	ds_bpermute_b32 v119, v164, v119
	ds_bpermute_b32 v120, v164, v120
	ds_bpermute_b32 v121, v164, v121
	v_lshl_add_u64 v[168:169], v[166:167], 0, v[116:117]
	s_waitcnt lgkmcnt(0)
	global_store_dwordx4 v[168:169], v[118:121], off nt
	s_and_saveexec_b64 s[22:23], s[0:1]
	s_cbranch_execz .LBB0_742
	global_store_dwordx4 v[114:115], v[110:113], off
	global_store_dwordx4 v[114:115], v[106:109], off offset:16
.LBB0_742:
	s_or_b64 exec, exec, s[22:23]
	s_nop 0
	v_cvt_pk_bf16_f32 v106, v102, v103
	v_cvt_pk_bf16_f32 v107, v104, v105
	v_cvt_pk_bf16_f32 v108, v98, v99
	v_cvt_pk_bf16_f32 v109, v100, v101
	ds_bpermute_b32 v106, v164, v106
	ds_bpermute_b32 v107, v164, v107
	ds_bpermute_b32 v108, v164, v108
	ds_bpermute_b32 v109, v164, v109
	v_lshl_add_u64 v[168:169], v[166:167], 0, v[116:117]
	s_waitcnt lgkmcnt(0)
	global_store_dwordx4 v[168:169], v[106:109], off offset:256 nt
	s_and_saveexec_b64 s[22:23], s[0:1]
	s_cbranch_execz .LBB0_744
	global_store_dwordx4 v[114:115], v[102:105], off offset:512
	global_store_dwordx4 v[114:115], v[98:101], off offset:528
.LBB0_744:
	s_or_b64 exec, exec, s[22:23]
	s_nop 0
	v_or_b32_e32 v100, 32, v159
	v_cmp_lt_i32_e64 s[0:1], s46, v100
	s_and_b64 s[22:23], s[0:1], s[18:19]
	v_mov_b64_e32 v[98:99], 0
	s_and_saveexec_b64 s[0:1], s[22:23]
	v_add_u32_e32 v98, 0xffffe020, v159
	v_lshrrev_b32_e32 v98, 2, v98
	v_and_b32_e32 v98, 0x3ffffffa, v98
	v_add_u32_e32 v101, v98, v154
	v_mov_b64_e32 v[98:99], s[10:11]
	v_mad_u64_u32 v[98:99], s[22:23], v101, s47, v[98:99]
	s_or_b64 exec, exec, s[0:1]
	v_mov_b64_e32 v[102:103], s[6:7]
	v_mad_i64_i32 v[100:101], s[0:1], v100, s48, v[102:103]
	v_lshl_add_u64 v[100:101], v[148:149], 1, v[100:101]
	v_cmp_ne_u64_e64 s[0:1], 0, v[98:99]
	v_lshl_add_u64 v[98:99], v[148:149], 2, v[98:99]
	v_cvt_pk_bf16_f32 v102, v94, v95
	v_cvt_pk_bf16_f32 v103, v96, v97
	v_cvt_pk_bf16_f32 v104, v90, v91
	v_cvt_pk_bf16_f32 v105, v92, v93
	ds_bpermute_b32 v102, v164, v102
	ds_bpermute_b32 v103, v164, v103
	ds_bpermute_b32 v104, v164, v104
	ds_bpermute_b32 v105, v164, v105
	v_lshl_add_u64 v[168:169], v[166:167], 0, v[100:101]
	s_waitcnt lgkmcnt(0)
	global_store_dwordx4 v[168:169], v[102:105], off nt
	s_and_saveexec_b64 s[22:23], s[0:1]
	s_cbranch_execz .LBB0_748
	global_store_dwordx4 v[98:99], v[94:97], off
	global_store_dwordx4 v[98:99], v[90:93], off offset:16
.LBB0_748:
	s_or_b64 exec, exec, s[22:23]
	s_nop 0
	v_cvt_pk_bf16_f32 v90, v86, v87
	v_cvt_pk_bf16_f32 v91, v88, v89
	v_cvt_pk_bf16_f32 v92, v82, v83
	v_cvt_pk_bf16_f32 v93, v84, v85
	ds_bpermute_b32 v90, v164, v90
	ds_bpermute_b32 v91, v164, v91
	ds_bpermute_b32 v92, v164, v92
	ds_bpermute_b32 v93, v164, v93
	v_lshl_add_u64 v[168:169], v[166:167], 0, v[100:101]
	s_waitcnt lgkmcnt(0)
	global_store_dwordx4 v[168:169], v[90:93], off offset:256 nt
	s_and_saveexec_b64 s[22:23], s[0:1]
	s_cbranch_execz .LBB0_750
	global_store_dwordx4 v[98:99], v[86:89], off offset:512
	global_store_dwordx4 v[98:99], v[82:85], off offset:528

.LBB0_758:
	s_or_b64 exec, exec, s[22:23]
	v_mov_b64_e32 v[86:87], s[6:7]
	v_mad_i64_i32 v[84:85], s[0:1], v84, s48, v[86:87]
	v_lshl_add_u64 v[84:85], v[148:149], 1, v[84:85]
	v_cmp_ne_u64_e64 s[0:1], 0, v[82:83]
	v_lshl_add_u64 v[82:83], v[148:149], 2, v[82:83]
	v_cvt_pk_bf16_f32 v86, v78, v79
	v_cvt_pk_bf16_f32 v87, v80, v81
	v_cvt_pk_bf16_f32 v88, v74, v75
	v_cvt_pk_bf16_f32 v89, v76, v77
	ds_bpermute_b32 v86, v164, v86
	ds_bpermute_b32 v87, v164, v87
	ds_bpermute_b32 v88, v164, v88
	ds_bpermute_b32 v89, v164, v89
	v_lshl_add_u64 v[168:169], v[166:167], 0, v[84:85]
	s_waitcnt lgkmcnt(0)
	global_store_dwordx4 v[168:169], v[86:89], off nt
	s_and_saveexec_b64 s[22:23], s[0:1]
	s_cbranch_execz .LBB0_760
	global_store_dwordx4 v[82:83], v[78:81], off
	global_store_dwordx4 v[82:83], v[74:77], off offset:16
.LBB0_760:
	s_or_b64 exec, exec, s[22:23]
	s_nop 0
	v_cvt_pk_bf16_f32 v74, v70, v71
	v_cvt_pk_bf16_f32 v75, v72, v73
	v_cvt_pk_bf16_f32 v76, v66, v67
	v_cvt_pk_bf16_f32 v77, v68, v69
	ds_bpermute_b32 v74, v164, v74
	ds_bpermute_b32 v75, v164, v75
	ds_bpermute_b32 v76, v164, v76
	ds_bpermute_b32 v77, v164, v77
	v_lshl_add_u64 v[168:169], v[166:167], 0, v[84:85]
	s_waitcnt lgkmcnt(0)
	global_store_dwordx4 v[168:169], v[74:77], off offset:256 nt
	s_and_saveexec_b64 s[22:23], s[0:1]
	s_cbranch_execz .LBB0_762
	global_store_dwordx4 v[82:83], v[70:73], off offset:512
	global_store_dwordx4 v[82:83], v[66:69], off offset:528
.LBB0_762:
	s_or_b64 exec, exec, s[22:23]
	v_cmp_lt_i32_e64 s[0:1], s51, v159
	s_and_b64 s[22:23], s[0:1], s[18:19]
	v_mov_b64_e32 v[66:67], 0
	s_and_saveexec_b64 s[0:1], s[22:23]
	v_add_u32_e32 v66, 0xffffe080, v159
	v_lshrrev_b32_e32 v66, 2, v66
	v_and_b32_e32 v66, 0x3ffffff2, v66
	v_add_u32_e32 v68, v66, v154
	v_mov_b64_e32 v[66:67], s[10:11]
	v_mad_u64_u32 v[66:67], s[22:23], v68, s47, v[66:67]
	s_or_b64 exec, exec, s[0:1]
	v_add_u32_e32 v70, 0x80, v159
	v_mov_b64_e32 v[68:69], s[6:7]
	v_mad_i64_i32 v[68:69], s[0:1], v70, s48, v[68:69]
	v_lshl_add_u64 v[68:69], v[148:149], 1, v[68:69]
	v_cmp_ne_u64_e64 s[0:1], 0, v[66:67]
	v_lshl_add_u64 v[66:67], v[148:149], 2, v[66:67]
	v_cvt_pk_bf16_f32 v72, v62, v63
	v_cvt_pk_bf16_f32 v73, v64, v65
	v_cvt_pk_bf16_f32 v74, v58, v59
	v_cvt_pk_bf16_f32 v75, v60, v61
	ds_bpermute_b32 v72, v164, v72
	ds_bpermute_b32 v73, v164, v73
	ds_bpermute_b32 v74, v164, v74
	ds_bpermute_b32 v75, v164, v75
	v_lshl_add_u64 v[168:169], v[166:167], 0, v[68:69]
	s_waitcnt lgkmcnt(0)
	global_store_dwordx4 v[168:169], v[72:75], off nt
	s_and_saveexec_b64 s[22:23], s[0:1]
	s_cbranch_execz .LBB0_766
	global_store_dwordx4 v[66:67], v[62:65], off
	global_store_dwordx4 v[66:67], v[58:61], off offset:16
.LBB0_766:
	s_or_b64 exec, exec, s[22:23]
	s_nop 0
	v_cvt_pk_bf16_f32 v58, v54, v55
	v_cvt_pk_bf16_f32 v59, v56, v57
	v_cvt_pk_bf16_f32 v60, v50, v51
	v_cvt_pk_bf16_f32 v61, v52, v53
	ds_bpermute_b32 v58, v164, v58
	ds_bpermute_b32 v59, v164, v59
	ds_bpermute_b32 v60, v164, v60
	ds_bpermute_b32 v61, v164, v61
	v_lshl_add_u64 v[168:169], v[166:167], 0, v[68:69]
	s_waitcnt lgkmcnt(0)
	global_store_dwordx4 v[168:169], v[58:61], off offset:256 nt
	s_and_saveexec_b64 s[22:23], s[0:1]
	s_cbranch_execz .LBB0_768
	global_store_dwordx4 v[66:67], v[54:57], off offset:512
	global_store_dwordx4 v[66:67], v[50:53], off offset:528
.LBB0_768:
	s_or_b64 exec, exec, s[22:23]
	v_cmp_lt_i32_e64 s[0:1], s52, v159
	s_and_b64 s[22:23], s[0:1], s[18:19]
	v_mov_b64_e32 v[50:51], 0
	s_and_saveexec_b64 s[0:1], s[22:23]
	v_add_u32_e32 v50, 0xffffe090, v159
	v_lshrrev_b32_e32 v50, 2, v50
	v_and_b32_e32 v50, 0x3ffffff6, v50
	v_add_u32_e32 v52, v50, v154
	v_mov_b64_e32 v[50:51], s[10:11]
	v_mad_u64_u32 v[50:51], s[22:23], v52, s47, v[50:51]
	s_or_b64 exec, exec, s[0:1]
	v_add_u32_e32 v54, 0x90, v159
	v_mov_b64_e32 v[52:53], s[6:7]
	v_mad_i64_i32 v[52:53], s[0:1], v54, s48, v[52:53]
	v_lshl_add_u64 v[52:53], v[148:149], 1, v[52:53]
	v_cmp_ne_u64_e64 s[0:1], 0, v[50:51]
	v_lshl_add_u64 v[50:51], v[148:149], 2, v[50:51]
	v_cvt_pk_bf16_f32 v54, v46, v47
	v_cvt_pk_bf16_f32 v55, v48, v49
	v_cvt_pk_bf16_f32 v56, v42, v43
	v_cvt_pk_bf16_f32 v57, v44, v45
	ds_bpermute_b32 v54, v164, v54
	ds_bpermute_b32 v55, v164, v55
	ds_bpermute_b32 v56, v164, v56
	ds_bpermute_b32 v57, v164, v57
	v_lshl_add_u64 v[168:169], v[166:167], 0, v[52:53]
	s_waitcnt lgkmcnt(0)
	global_store_dwordx4 v[168:169], v[54:57], off nt
	s_and_saveexec_b64 s[22:23], s[0:1]
	s_cbranch_execz .LBB0_772
	global_store_dwordx4 v[50:51], v[46:49], off
	global_store_dwordx4 v[50:51], v[42:45], off offset:16
.LBB0_772:
	s_or_b64 exec, exec, s[22:23]
	s_nop 0
	v_cvt_pk_bf16_f32 v42, v38, v39
	v_cvt_pk_bf16_f32 v43, v40, v41
	v_cvt_pk_bf16_f32 v44, v34, v35
	v_cvt_pk_bf16_f32 v45, v36, v37
	ds_bpermute_b32 v42, v164, v42
	ds_bpermute_b32 v43, v164, v43
	ds_bpermute_b32 v44, v164, v44
	ds_bpermute_b32 v45, v164, v45
	v_lshl_add_u64 v[168:169], v[166:167], 0, v[52:53]
	s_waitcnt lgkmcnt(0)
	global_store_dwordx4 v[168:169], v[42:45], off offset:256 nt
	s_and_saveexec_b64 s[22:23], s[0:1]
	s_cbranch_execz .LBB0_774
	global_store_dwordx4 v[50:51], v[38:41], off offset:512
	global_store_dwordx4 v[50:51], v[34:37], off offset:528
.LBB0_774:
	s_or_b64 exec, exec, s[22:23]
	v_cmp_lt_i32_e64 s[0:1], s53, v159
	s_and_b64 s[22:23], s[0:1], s[18:19]
	v_mov_b64_e32 v[34:35], 0
	s_and_saveexec_b64 s[0:1], s[22:23]
	v_add_u32_e32 v34, 0xffffe0a0, v159
	v_lshrrev_b32_e32 v34, 2, v34
	v_and_b32_e32 v34, 0x3ffffffa, v34
	v_add_u32_e32 v36, v34, v154
	v_mov_b64_e32 v[34:35], s[10:11]
	v_mad_u64_u32 v[34:35], s[22:23], v36, s47, v[34:35]
	s_or_b64 exec, exec, s[0:1]
	v_add_u32_e32 v38, 0xa0, v159
	v_mov_b64_e32 v[36:37], s[6:7]
	v_mad_i64_i32 v[36:37], s[0:1], v38, s48, v[36:37]
	v_lshl_add_u64 v[36:37], v[148:149], 1, v[36:37]
	v_cmp_ne_u64_e64 s[0:1], 0, v[34:35]
	v_lshl_add_u64 v[34:35], v[148:149], 2, v[34:35]
	v_cvt_pk_bf16_f32 v38, v30, v31
	v_cvt_pk_bf16_f32 v39, v32, v33
	v_cvt_pk_bf16_f32 v40, v26, v27
	v_cvt_pk_bf16_f32 v41, v28, v29
	ds_bpermute_b32 v38, v164, v38
	ds_bpermute_b32 v39, v164, v39
	ds_bpermute_b32 v40, v164, v40
	ds_bpermute_b32 v41, v164, v41
	v_lshl_add_u64 v[168:169], v[166:167], 0, v[36:37]
	s_waitcnt lgkmcnt(0)
	global_store_dwordx4 v[168:169], v[38:41], off nt
	s_and_saveexec_b64 s[22:23], s[0:1]
	s_cbranch_execz .LBB0_778
	global_store_dwordx4 v[34:35], v[30:33], off
	global_store_dwordx4 v[34:35], v[26:29], off offset:16
.LBB0_778:
	s_or_b64 exec, exec, s[22:23]
	s_nop 0
	v_cvt_pk_bf16_f32 v26, v22, v23
	v_cvt_pk_bf16_f32 v27, v24, v25
	v_cvt_pk_bf16_f32 v28, v18, v19
	v_cvt_pk_bf16_f32 v29, v20, v21
	ds_bpermute_b32 v26, v164, v26
	ds_bpermute_b32 v27, v164, v27
	ds_bpermute_b32 v28, v164, v28
	ds_bpermute_b32 v29, v164, v29
	v_lshl_add_u64 v[168:169], v[166:167], 0, v[36:37]
	s_waitcnt lgkmcnt(0)
	global_store_dwordx4 v[168:169], v[26:29], off offset:256 nt
	s_and_saveexec_b64 s[22:23], s[0:1]
	s_cbranch_execz .LBB0_780
	global_store_dwordx4 v[34:35], v[22:25], off offset:512
	global_store_dwordx4 v[34:35], v[18:21], off offset:528

.LBB0_788:
	s_or_b64 exec, exec, s[22:23]
	v_mov_b64_e32 v[22:23], s[6:7]
	v_mad_i64_i32 v[20:21], s[0:1], v20, s48, v[22:23]
	v_lshl_add_u64 v[20:21], v[148:149], 1, v[20:21]
	v_cmp_ne_u64_e64 s[0:1], 0, v[18:19]
	v_lshl_add_u64 v[18:19], v[148:149], 2, v[18:19]
	v_cvt_pk_bf16_f32 v22, v14, v15
	v_cvt_pk_bf16_f32 v23, v16, v17
	v_cvt_pk_bf16_f32 v24, v10, v11
	v_cvt_pk_bf16_f32 v25, v12, v13
	ds_bpermute_b32 v22, v164, v22
	ds_bpermute_b32 v23, v164, v23
	ds_bpermute_b32 v24, v164, v24
	ds_bpermute_b32 v25, v164, v25
	v_lshl_add_u64 v[168:169], v[166:167], 0, v[20:21]
	s_waitcnt lgkmcnt(0)
	global_store_dwordx4 v[168:169], v[22:25], off nt
	s_and_saveexec_b64 s[22:23], s[0:1]
	s_cbranch_execz .LBB0_790
	global_store_dwordx4 v[18:19], v[14:17], off
	global_store_dwordx4 v[18:19], v[10:13], off offset:16
.LBB0_790:
	s_or_b64 exec, exec, s[22:23]
	s_nop 0
	v_cvt_pk_bf16_f32 v10, v6, v7
	v_cvt_pk_bf16_f32 v11, v8, v9
	v_cvt_pk_bf16_f32 v12, v2, v3
	v_cvt_pk_bf16_f32 v13, v4, v5
	ds_bpermute_b32 v10, v164, v10
	ds_bpermute_b32 v11, v164, v11
	ds_bpermute_b32 v12, v164, v12
	ds_bpermute_b32 v13, v164, v13
	v_lshl_add_u64 v[168:169], v[166:167], 0, v[20:21]
	s_waitcnt lgkmcnt(0)
	global_store_dwordx4 v[168:169], v[10:13], off offset:256 nt
	s_and_saveexec_b64 s[22:23], s[0:1]
	s_cbranch_execz .LBB0_729
	global_store_dwordx4 v[18:19], v[6:9], off offset:512
	global_store_dwordx4 v[18:19], v[2:5], off offset:528
	s_branch .LBB0_729
